# grid barrier leader tail: the never-read per-XCD generation atomic (and the round trip the XCD leader waited for it) removed at all 8 sites
# speedup vs baseline: 1.0037x; 1.0037x over previous
; DI unsigned xb_add(unsigned* p, unsigned v) { return __hip_atomic_fetch_add(p, v, __ATOMIC_RELAXED, __HIP_MEMORY_SCOPE_AGENT); }
; DI void xcd_barrier(const XcdBarrier& b) {
;     ...
;             __builtin_amdgcn_fence(__ATOMIC_ACQUIRE, "agent");
;             xb_add(&bar[XB_XGEN(b.x)], 1u);
;             asm volatile("s_waitcnt vmcnt(0)" ::: "memory");
.LBB0_91:
	s_or_b64 exec, exec, s[4:5]
	s_mov_b64 s[4:5], exec
	v_mbcnt_lo_u32_b32 v1, s4, 0
	v_mbcnt_hi_u32_b32 v1, s5, v1
	v_cmp_eq_u32_e32 vcc, 0, v1
	s_waitcnt vmcnt(0)
	buffer_inv sc1
	s_and_saveexec_b64 s[10:11], vcc
	s_cbranch_execz .LBB0_93
	s_bcnt1_i32_b64 s4, s[4:5]
	v_mov_b32_e32 v1, 0x2000
	v_mov_b32_e32 v2, s4


; DI unsigned xb_add(unsigned* p, unsigned v) { return __hip_atomic_fetch_add(p, v, __ATOMIC_RELAXED, __HIP_MEMORY_SCOPE_AGENT); }
; DI void xcd_barrier(const XcdBarrier& b) {
;     ...
;             __builtin_amdgcn_fence(__ATOMIC_ACQUIRE, "agent");
;             xb_add(&bar[XB_XGEN(b.x)], 1u);
;             asm volatile("s_waitcnt vmcnt(0)" ::: "memory");
.LBB0_195:
	s_or_b64 exec, exec, s[40:41]
	s_mov_b64 s[40:41], exec
	v_mbcnt_lo_u32_b32 v0, s40, 0
	v_mbcnt_hi_u32_b32 v0, s41, v0
	v_cmp_eq_u32_e32 vcc, 0, v0
	s_waitcnt vmcnt(0)
	buffer_inv sc1
	s_and_saveexec_b64 s[42:43], vcc
	s_cbranch_execz .LBB0_197
	s_bcnt1_i32_b64 s6, s[40:41]
	v_readlane_b32 s8, v251, 6
	v_mov_b32_e32 v0, s6
	v_readlane_b32 s9, v251, 7
	s_nop 4


; DI unsigned xb_add(unsigned* p, unsigned v) { return __hip_atomic_fetch_add(p, v, __ATOMIC_RELAXED, __HIP_MEMORY_SCOPE_AGENT); }
; DI void xcd_barrier(const XcdBarrier& b) {
;     ...
;             __builtin_amdgcn_fence(__ATOMIC_ACQUIRE, "agent");
;             xb_add(&bar[XB_XGEN(b.x)], 1u);
;             asm volatile("s_waitcnt vmcnt(0)" ::: "memory");
.LBB0_366:
	s_or_b64 exec, exec, s[12:13]
	s_mov_b64 s[12:13], exec
	v_mbcnt_lo_u32_b32 v0, s12, 0
	v_mbcnt_hi_u32_b32 v0, s13, v0
	v_cmp_eq_u32_e32 vcc, 0, v0
	s_waitcnt vmcnt(0)
	buffer_inv sc1
	s_and_saveexec_b64 s[40:41], vcc
	s_cbranch_execz .LBB0_368
	s_bcnt1_i32_b64 s6, s[12:13]
	v_readlane_b32 s12, v251, 6
	v_mov_b32_e32 v0, s6
	v_readlane_b32 s13, v251, 7
	s_nop 4


; DI unsigned xb_add(unsigned* p, unsigned v) { return __hip_atomic_fetch_add(p, v, __ATOMIC_RELAXED, __HIP_MEMORY_SCOPE_AGENT); }
; DI void xcd_barrier(const XcdBarrier& b) {
;     ...
;             __builtin_amdgcn_fence(__ATOMIC_ACQUIRE, "agent");
;             xb_add(&bar[XB_XGEN(b.x)], 1u);
;             asm volatile("s_waitcnt vmcnt(0)" ::: "memory");
.LBB0_973:
	s_or_b64 exec, exec, s[2:3]
	s_mov_b64 s[2:3], exec
	v_mbcnt_lo_u32_b32 v0, s2, 0
	v_mbcnt_hi_u32_b32 v0, s3, v0
	v_cmp_eq_u32_e32 vcc, 0, v0
	s_waitcnt vmcnt(0)
	buffer_inv sc1
	s_and_saveexec_b64 s[4:5], vcc
	s_cbranch_execz .LBB0_975
	s_bcnt1_i32_b64 s2, s[2:3]
	v_mov_b32_e32 v1, s2
	v_readlane_b32 s2, v251, 6
	v_mov_b32_e32 v0, 0
	v_readlane_b32 s3, v251, 7
	s_nop 4

